# attn_b v4: reference raised only when a lane's tile row-sum exceeds 2^64 (max tree moved to the rare path)
# speedup vs baseline: 1.0188x; 1.0188x over previous
.LBB0_641:
	s_ashr_i32 s0, s5, 7
	s_mul_i32 s23, s0, 0x3e00000
	s_mul_hi_i32 s17, s0, 0x3e00000
	s_add_u32 s0, s2, s23
	s_addc_u32 s1, s4, s17
	s_lshl_b32 s8, s5, 8
	s_and_b32 s8, s8, 0xf00
	v_and_b32_e32 v32, 15, v2
	v_lshl_add_u32 v0, v0, 5, s8
	s_waitcnt lgkmcnt(0)
	v_or_b32_e32 v3, v0, v32
	v_mov_b64_e32 v[4:5], s[0:1]
	v_mad_i64_i32 v[6:7], s[0:1], v3, s65, v[4:5]
	s_lshl_b32 s0, s5, 3
	v_or_b32_e32 v3, 16, v3
	s_and_b32 s8, s0, 0x380
	v_mad_i64_i32 v[8:9], s[0:1], v3, s65, v[4:5]
	v_ashrrev_i32_e32 v3, 3, v2
	s_waitcnt lgkmcnt(0)
	v_bfe_u32 v33, v2, 4, 2
	v_lshl_add_u64 v[6:7], v[6:7], 0, s[8:9]
	s_mov_b64 s[12:13], 0x1000
	v_lshl_add_u64 v[8:9], v[8:9], 0, s[8:9]
	v_mad_i64_i32 v[4:5], s[0:1], v3, s65, v[4:5]
	v_lshl_add_u64 v[110:111], v[6:7], 0, s[12:13]
	v_lshlrev_b32_e32 v0, 4, v33
	v_lshl_add_u64 v[108:109], v[8:9], 0, s[12:13]
	s_and_b32 s0, s5, 64
	v_lshl_add_u64 v[6:7], v[110:111], 0, v[0:1]
	v_lshl_add_u64 v[28:29], v[108:109], 0, v[0:1]
	s_lshl_b32 s8, s0, 1
	v_lshlrev_b32_e32 v0, 4, v2
	v_and_b32_e32 v0, 0x70, v0
	v_lshl_add_u64 v[4:5], v[4:5], 0, s[8:9]
	v_lshl_add_u64 v[30:31], v[4:5], 0, v[0:1]
	v_add_co_u32_e32 v4, vcc, s71, v30
	v_lshlrev_b32_e32 v118, 2, v33
	s_nop 0
	v_addc_co_u32_e32 v5, vcc, 0, v31, vcc
	global_load_dwordx4 v[20:23], v[4:5], off offset:1024
	global_load_dwordx4 v[24:27], v[4:5], off offset:1280
	global_load_dwordx4 v[16:19], v[6:7], off
	global_load_dwordx4 v[8:11], v[6:7], off offset:64
	global_load_dwordx4 v[12:15], v[28:29], off
	s_nop 0
	global_load_dwordx4 v[4:7], v[28:29], off offset:64
	v_bfe_u32 v29, v2, 2, 2
	v_lshlrev_b32_e32 v28, 3, v2
	v_or_b32_e32 v29, v118, v29
	s_mov_b64 s[18:19], 0x1400
	v_lshlrev_b32_e32 v34, 3, v33
	v_mul_lo_u32 v35, v3, s40
	v_mul_u32_u24_e32 v32, 0x50, v32
	v_and_b32_e32 v28, 24, v28
	v_mul_u32_u24_e32 v29, 0xa0, v29
	v_lshl_add_u64 v[112:113], v[30:31], 0, s[18:19]
	s_mov_b64 s[18:19], 0x1500
	s_mov_b64 s[88:89], 0x1000
	s_mov_b64 s[0:1], -1
	v_lshlrev_b32_e32 v116, 1, v32
	v_add3_u32 v119, 0, v29, v28
	s_cmp_lt_i32 s30, 4
	v_add3_u32 v120, 0, v35, v0
	v_lshl_add_u64 v[114:115], v[30:31], 0, s[18:19]
	v_lshlrev_b32_e32 v0, 1, v34
	s_barrier
	s_waitcnt vmcnt(5)
	ds_write_b128 v120, v[20:23]
	s_waitcnt vmcnt(4)
	ds_write_b128 v120, v[24:27] offset:20480
	s_waitcnt lgkmcnt(0)
	s_barrier
	s_cbranch_scc1 .Lb_groupA
	s_waitcnt vmcnt(0)
	v_mov_b32_e32 v34, 0
	v_mov_b32_e32 v35, 0
	v_mov_b32_e32 v36, 0
	v_mov_b32_e32 v37, 0
	v_mov_b32_e32 v42, 0
	v_mov_b32_e32 v43, 0
	v_mov_b32_e32 v44, 0
	v_mov_b32_e32 v45, 0
	v_mov_b32_e32 v56, 0
	v_mov_b32_e32 v57, 0
	v_mov_b32_e32 v58, 0
	v_mov_b32_e32 v59, 0
	v_mov_b32_e32 v60, 0
	v_mov_b32_e32 v61, 0
	v_mov_b32_e32 v62, 0
	v_mov_b32_e32 v63, 0
	v_mov_b32_e32 v20, 0
	v_mov_b32_e32 v21, 0
	v_mov_b32_e32 v22, 0
	v_mov_b32_e32 v23, 0
	v_mov_b32_e32 v24, 0
	v_mov_b32_e32 v25, 0
	v_mov_b32_e32 v26, 0
	v_mov_b32_e32 v27, 0
	v_mov_b32_e32 v38, 0
	v_mov_b32_e32 v39, 0
	v_mov_b32_e32 v40, 0
	v_mov_b32_e32 v41, 0
	v_mov_b32_e32 v28, 0
	v_mov_b32_e32 v29, 0
	v_mov_b32_e32 v30, 0
	v_mov_b32_e32 v31, 0
	v_mov_b32_e32 v180, 0
	v_mov_b32_e32 v181, 0
	v_mov_b32_e32 v182, 0
	v_mov_b32_e32 v183, 0
	v_mov_b32_e32 v184, 0
	v_mov_b32_e32 v185, 0
	v_mov_b32_e32 v186, 0
	v_mov_b32_e32 v187, 0
	v_mov_b32_e32 v188, 0
	v_mov_b32_e32 v189, 0
	v_mov_b32_e32 v190, 0
	v_mov_b32_e32 v191, 0
	v_mov_b32_e32 v204, 0
	v_mov_b32_e32 v205, 0
	v_mov_b32_e32 v206, 0
	v_mov_b32_e32 v207, 0
	v_mov_b32_e32 v48, 0
	v_mov_b32_e32 v49, 0
	v_mov_b32_e32 v50, 0
	v_mov_b32_e32 v51, 0
	v_mov_b32_e32 v52, 0
	v_mov_b32_e32 v53, 0
	v_mov_b32_e32 v54, 0
	v_mov_b32_e32 v55, 0
	v_mov_b32_e32 v80, 0
	v_mov_b32_e32 v64, 0
	v_add_u32_e32 v75, v116, v0
	s_mov_b32 s20, 0
	s_mov_b32 s42, 0
	s_mov_b32 s43, 0
	s_mov_b32 s51, 10240
	s_mov_b32 s30, 0xf8000
	s_mov_b32 s66, 0xff800000
	s_mov_b32 s67, 0xff800000
	v_mov_b32_e32 v88, 0xff800000
	v_mov_b32_e32 v89, 0xff800000
	v_mov_b32_e32 v90, 0xff800000
	v_mov_b32_e32 v91, 0xff800000
	v_mov_b32_e32 v92, 0xff800000
	v_mov_b32_e32 v93, 0xff800000
	v_mov_b32_e32 v94, 0xff800000
	v_mov_b32_e32 v95, 0xff800000
	v_mov_b32_e32 v96, 0xff800000
	v_mov_b32_e32 v97, 0xff800000
	v_mov_b32_e32 v98, 0xff800000
	v_mov_b32_e32 v99, 0xff800000
	v_mov_b32_e32 v100, 0xff800000
	v_mov_b32_e32 v101, 0xff800000
	v_mov_b32_e32 v102, 0xff800000
	v_mov_b32_e32 v103, 0xff800000
	v_mov_b32_e32 v104, 0xff800000
	v_mov_b32_e32 v105, 0xff800000
	v_mov_b32_e32 v106, 0xff800000
	v_mov_b32_e32 v107, 0xff800000
	v_mov_b32_e32 v168, 0xff800000
	v_mov_b32_e32 v169, 0xff800000
	v_mov_b32_e32 v170, 0xff800000
	v_mov_b32_e32 v171, 0xff800000
	v_mov_b32_e32 v172, 0xff800000
	v_mov_b32_e32 v173, 0xff800000
	v_mov_b32_e32 v174, 0xff800000
	v_mov_b32_e32 v175, 0xff800000
	v_mov_b32_e32 v176, 0xff800000
	v_mov_b32_e32 v177, 0xff800000
	v_mov_b32_e32 v178, 0xff800000
	v_mov_b32_e32 v179, 0xff800000
.Lb_loopB:
	s_and_b32 s8, s20, 1
	s_mul_i32 s32, s8, 10240
	s_xor_b32 s8, s8, 1
	s_mul_i32 s8, s8, 10240
	v_add_u32_e32 v71, s32, v75
	v_add_u32_e32 v73, s8, v120
	v_add_u32_e32 v72, s42, v119
	v_add_u32_e32 v74, s51, v120
	s_mov_b32 s19, 0
	s_mov_b32 s18, s30
	v_lshl_add_u64 v[208:209], v[112:113], 0, s[18:19]
	v_lshl_add_u64 v[212:213], v[114:115], 0, s[18:19]
	global_load_dwordx4 v[208:211], v[208:209], off
	global_load_dwordx4 v[212:215], v[212:213], off
	ds_read_b128 v[216:219], v71 offset:0
	ds_read_b128 v[220:223], v71 offset:64
	ds_read_b128 v[224:227], v71 offset:2560
	ds_read_b128 v[228:231], v71 offset:2624
	v_exp_f32_e32 v236, v88
	v_exp_f32_e32 v237, v89
	v_exp_f32_e32 v238, v90
	v_exp_f32_e32 v239, v91
	v_exp_f32_e32 v240, v92
	v_exp_f32_e32 v241, v93
	v_exp_f32_e32 v242, v94
	v_exp_f32_e32 v243, v95
	v_exp_f32_e32 v244, v96
	v_exp_f32_e32 v245, v97
	v_exp_f32_e32 v246, v98
	v_exp_f32_e32 v247, v99
	v_exp_f32_e32 v248, v100
	v_exp_f32_e32 v249, v101
	v_exp_f32_e32 v250, v102
	v_exp_f32_e32 v251, v103
	s_nop 0
	v_add_f32_e32 v67, v236, v237
	v_add_f32_e32 v67, v67, v238
	v_add_f32_e32 v67, v67, v239
	v_add_f32_e32 v67, v67, v240
	v_add_f32_e32 v67, v67, v241
	v_add_f32_e32 v67, v67, v242
	v_add_f32_e32 v67, v67, v243
	v_add_f32_e32 v67, v67, v244
	v_add_f32_e32 v67, v67, v245
	v_add_f32_e32 v67, v67, v246
	v_add_f32_e32 v67, v67, v247
	v_add_f32_e32 v67, v67, v248
	v_add_f32_e32 v67, v67, v249
	v_add_f32_e32 v67, v67, v250
	v_add_f32_e32 v67, v67, v251
	v_cmp_lt_f32_e32 vcc, s66, v67
	s_cbranch_vccnz .Lb_rare_B_0
.Lb_back_B_0:
	v_add_f32_e32 v80, v80, v67
	v_cvt_pk_bf16_f32 v180, v236, v237
	v_cvt_pk_bf16_f32 v181, v238, v239
	v_cvt_pk_bf16_f32 v182, v240, v241
	v_cvt_pk_bf16_f32 v183, v242, v243
	v_cvt_pk_bf16_f32 v188, v244, v245
	v_cvt_pk_bf16_f32 v189, v246, v247
	v_cvt_pk_bf16_f32 v190, v248, v249
	v_cvt_pk_bf16_f32 v191, v250, v251
	v_exp_f32_e32 v236, v104
	v_exp_f32_e32 v237, v105
	v_exp_f32_e32 v238, v106
	v_exp_f32_e32 v239, v107
	v_exp_f32_e32 v240, v168
	v_exp_f32_e32 v241, v169
	v_exp_f32_e32 v242, v170
	v_exp_f32_e32 v243, v171
	v_exp_f32_e32 v244, v172
	v_exp_f32_e32 v245, v173
	v_exp_f32_e32 v246, v174
	v_exp_f32_e32 v247, v175
	v_exp_f32_e32 v248, v176
	v_exp_f32_e32 v249, v177
	v_exp_f32_e32 v250, v178
	v_exp_f32_e32 v251, v179
	s_nop 0
	v_add_f32_e32 v67, v236, v237
	v_add_f32_e32 v67, v67, v238
	v_add_f32_e32 v67, v67, v239
	v_add_f32_e32 v67, v67, v240
	v_add_f32_e32 v67, v67, v241
	v_add_f32_e32 v67, v67, v242
	v_add_f32_e32 v67, v67, v243
	v_add_f32_e32 v67, v67, v244
	v_add_f32_e32 v67, v67, v245
	v_add_f32_e32 v67, v67, v246
	v_add_f32_e32 v67, v67, v247
	v_add_f32_e32 v67, v67, v248
	v_add_f32_e32 v67, v67, v249
	v_add_f32_e32 v67, v67, v250
	v_add_f32_e32 v67, v67, v251
	v_cmp_lt_f32_e32 vcc, s66, v67
	s_cbranch_vccnz .Lb_rare_B_1
.Lb_back_B_1:
	v_add_f32_e32 v64, v64, v67
	v_cvt_pk_bf16_f32 v184, v236, v237
	v_cvt_pk_bf16_f32 v185, v238, v239
	v_cvt_pk_bf16_f32 v186, v240, v241
	v_cvt_pk_bf16_f32 v187, v242, v243
	v_cvt_pk_bf16_f32 v204, v244, v245
	v_cvt_pk_bf16_f32 v205, v246, v247
	v_cvt_pk_bf16_f32 v206, v248, v249
	v_cvt_pk_bf16_f32 v207, v250, v251
	ds_read_b128 v[232:235], v71 offset:5120
	s_waitcnt lgkmcnt(4)
	v_mfma_f32_16x16x32_bf16 v[88:91], v[216:219], v[16:19], v[48:51]
	v_mfma_f32_16x16x32_bf16 v[104:107], v[216:219], v[12:15], v[52:55]
	ds_read_b128 v[216:219], v71 offset:5184
	s_waitcnt lgkmcnt(4)
	v_mfma_f32_16x16x32_bf16 v[88:91], v[220:223], v[8:11], v[88:91]
	v_mfma_f32_16x16x32_bf16 v[104:107], v[220:223], v[4:7], v[104:107]
	ds_read_b128 v[220:223], v71 offset:7680
	s_waitcnt lgkmcnt(4)
	v_mfma_f32_16x16x32_bf16 v[92:95], v[224:227], v[16:19], v[48:51]
	v_mfma_f32_16x16x32_bf16 v[168:171], v[224:227], v[12:15], v[52:55]
	ds_read_b128 v[224:227], v71 offset:7744
	s_waitcnt lgkmcnt(4)
	v_mfma_f32_16x16x32_bf16 v[92:95], v[228:231], v[8:11], v[92:95]
	v_mfma_f32_16x16x32_bf16 v[168:171], v[228:231], v[4:7], v[168:171]
	ds_read_b64_tr_b16 v[228:229], v72 offset:20480
	ds_read_b64_tr_b16 v[230:231], v72 offset:23040
	s_waitcnt lgkmcnt(5)
	v_mfma_f32_16x16x32_bf16 v[96:99], v[232:235], v[16:19], v[48:51]
	v_mfma_f32_16x16x32_bf16 v[172:175], v[232:235], v[12:15], v[52:55]
	ds_read_b64_tr_b16 v[232:233], v72 offset:20512
	ds_read_b64_tr_b16 v[234:235], v72 offset:23072
	s_waitcnt lgkmcnt(6)
	v_mfma_f32_16x16x32_bf16 v[96:99], v[216:219], v[8:11], v[96:99]
	v_mfma_f32_16x16x32_bf16 v[172:175], v[216:219], v[4:7], v[172:175]
	ds_read_b64_tr_b16 v[216:217], v72 offset:20544
	ds_read_b64_tr_b16 v[218:219], v72 offset:23104
	s_waitcnt lgkmcnt(7)
	v_mfma_f32_16x16x32_bf16 v[100:103], v[220:223], v[16:19], v[48:51]
	v_mfma_f32_16x16x32_bf16 v[176:179], v[220:223], v[12:15], v[52:55]
	ds_read_b64_tr_b16 v[220:221], v72 offset:20576
	ds_read_b64_tr_b16 v[222:223], v72 offset:23136
	s_waitcnt lgkmcnt(8)
	v_mfma_f32_16x16x32_bf16 v[100:103], v[224:227], v[8:11], v[100:103]
	v_mfma_f32_16x16x32_bf16 v[176:179], v[224:227], v[4:7], v[176:179]
	ds_read_b64_tr_b16 v[224:225], v72 offset:25600
	ds_read_b64_tr_b16 v[226:227], v72 offset:28160
	s_waitcnt lgkmcnt(8)
	v_mfma_f32_16x16x32_bf16 v[34:37], v[228:231], v[180:183], v[34:37]
	v_mfma_f32_16x16x32_bf16 v[20:23], v[228:231], v[184:187], v[20:23]
	ds_read_b64_tr_b16 v[228:229], v72 offset:25632
	ds_read_b64_tr_b16 v[230:231], v72 offset:28192
	s_waitcnt lgkmcnt(8)
	v_mfma_f32_16x16x32_bf16 v[42:45], v[232:235], v[180:183], v[42:45]
	v_mfma_f32_16x16x32_bf16 v[24:27], v[232:235], v[184:187], v[24:27]
	ds_read_b64_tr_b16 v[232:233], v72 offset:25664
	ds_read_b64_tr_b16 v[234:235], v72 offset:28224
	s_waitcnt lgkmcnt(8)
	v_mfma_f32_16x16x32_bf16 v[56:59], v[216:219], v[180:183], v[56:59]
	v_mfma_f32_16x16x32_bf16 v[38:41], v[216:219], v[184:187], v[38:41]
	ds_read_b64_tr_b16 v[216:217], v72 offset:25696
	ds_read_b64_tr_b16 v[218:219], v72 offset:28256
	s_waitcnt lgkmcnt(8)
	v_mfma_f32_16x16x32_bf16 v[60:63], v[220:223], v[180:183], v[60:63]
	v_mfma_f32_16x16x32_bf16 v[28:31], v[220:223], v[184:187], v[28:31]
	s_waitcnt lgkmcnt(6)
	v_mfma_f32_16x16x32_bf16 v[34:37], v[224:227], v[188:191], v[34:37]
	v_mfma_f32_16x16x32_bf16 v[20:23], v[224:227], v[204:207], v[20:23]
	s_waitcnt lgkmcnt(4)
	v_mfma_f32_16x16x32_bf16 v[42:45], v[228:231], v[188:191], v[42:45]
	v_mfma_f32_16x16x32_bf16 v[24:27], v[228:231], v[204:207], v[24:27]
	s_waitcnt lgkmcnt(2)
	v_mfma_f32_16x16x32_bf16 v[56:59], v[232:235], v[188:191], v[56:59]
	v_mfma_f32_16x16x32_bf16 v[38:41], v[232:235], v[204:207], v[38:41]
	s_waitcnt lgkmcnt(0)
	v_mfma_f32_16x16x32_bf16 v[60:63], v[216:219], v[188:191], v[60:63]
	v_mfma_f32_16x16x32_bf16 v[28:31], v[216:219], v[204:207], v[28:31]
	s_waitcnt vmcnt(0)
	ds_write_b128 v73, v[208:211]
	ds_write_b128 v74, v[212:215] offset:20480
	s_mov_b32 s42, s43
	s_mov_b32 s43, s51
	s_add_i32 s51, s51, 10240
	s_cmp_lg_u32 s51, 30720
	s_cselect_b32 s51, s51, 0
	s_mov_b32 s66, 0xff800000
	s_mov_b32 s67, 0xff800000
	s_cmp_ge_u32 s20, 1
	s_cselect_b32 s66, 0x5f800000, s66
	s_cselect_b32 s67, 0x42000000, s67
	s_add_i32 s20, s20, 1
	s_min_u32 s8, s20, 62
	s_add_i32 s8, s8, 1
	s_mul_i32 s30, s8, 0xf8000
	s_waitcnt lgkmcnt(0)
	s_barrier
	s_cmp_lt_u32 s20, 64
	s_cbranch_scc1 .Lb_loopB
	v_add_u32_e32 v72, s42, v119
	ds_read_b64_tr_b16 v[216:217], v72 offset:20480
	ds_read_b64_tr_b16 v[218:219], v72 offset:23040
	ds_read_b64_tr_b16 v[220:221], v72 offset:20512
	ds_read_b64_tr_b16 v[222:223], v72 offset:23072
	ds_read_b64_tr_b16 v[224:225], v72 offset:20544
	ds_read_b64_tr_b16 v[226:227], v72 offset:23104
	ds_read_b64_tr_b16 v[228:229], v72 offset:20576
	ds_read_b64_tr_b16 v[230:231], v72 offset:23136
	v_exp_f32_e32 v236, v88
	v_exp_f32_e32 v237, v89
	v_exp_f32_e32 v238, v90
	v_exp_f32_e32 v239, v91
	v_exp_f32_e32 v240, v92
	v_exp_f32_e32 v241, v93
	v_exp_f32_e32 v242, v94
	v_exp_f32_e32 v243, v95
	v_exp_f32_e32 v244, v96
	v_exp_f32_e32 v245, v97
	v_exp_f32_e32 v246, v98
	v_exp_f32_e32 v247, v99
	v_exp_f32_e32 v248, v100
	v_exp_f32_e32 v249, v101
	v_exp_f32_e32 v250, v102
	v_exp_f32_e32 v251, v103
	s_nop 0
	v_add_f32_e32 v67, v236, v237
	v_add_f32_e32 v67, v67, v238
	v_add_f32_e32 v67, v67, v239
	v_add_f32_e32 v67, v67, v240
	v_add_f32_e32 v67, v67, v241
	v_add_f32_e32 v67, v67, v242
	v_add_f32_e32 v67, v67, v243
	v_add_f32_e32 v67, v67, v244
	v_add_f32_e32 v67, v67, v245
	v_add_f32_e32 v67, v67, v246
	v_add_f32_e32 v67, v67, v247
	v_add_f32_e32 v67, v67, v248
	v_add_f32_e32 v67, v67, v249
	v_add_f32_e32 v67, v67, v250
	v_add_f32_e32 v67, v67, v251
	v_cmp_lt_f32_e32 vcc, s66, v67
	s_cbranch_vccnz .Lb_rare_Bt_0

.Lb_back_Bt_1:
	v_add_f32_e32 v64, v64, v67
	v_cvt_pk_bf16_f32 v184, v236, v237
	v_cvt_pk_bf16_f32 v185, v238, v239
	v_cvt_pk_bf16_f32 v186, v240, v241
	v_cvt_pk_bf16_f32 v187, v242, v243
	v_cvt_pk_bf16_f32 v204, v244, v245
	v_cvt_pk_bf16_f32 v205, v246, v247
	v_cvt_pk_bf16_f32 v206, v248, v249
	v_cvt_pk_bf16_f32 v207, v250, v251
	ds_read_b64_tr_b16 v[232:233], v72 offset:25600
	ds_read_b64_tr_b16 v[234:235], v72 offset:28160
	s_waitcnt lgkmcnt(8)
	v_mfma_f32_16x16x32_bf16 v[34:37], v[216:219], v[180:183], v[34:37]
	v_mfma_f32_16x16x32_bf16 v[20:23], v[216:219], v[184:187], v[20:23]
	ds_read_b64_tr_b16 v[216:217], v72 offset:25632
	ds_read_b64_tr_b16 v[218:219], v72 offset:28192
	s_waitcnt lgkmcnt(8)
	v_mfma_f32_16x16x32_bf16 v[42:45], v[220:223], v[180:183], v[42:45]
	v_mfma_f32_16x16x32_bf16 v[24:27], v[220:223], v[184:187], v[24:27]
	ds_read_b64_tr_b16 v[220:221], v72 offset:25664
	ds_read_b64_tr_b16 v[222:223], v72 offset:28224
	s_waitcnt lgkmcnt(8)
	v_mfma_f32_16x16x32_bf16 v[56:59], v[224:227], v[180:183], v[56:59]
	v_mfma_f32_16x16x32_bf16 v[38:41], v[224:227], v[184:187], v[38:41]
	ds_read_b64_tr_b16 v[224:225], v72 offset:25696
	ds_read_b64_tr_b16 v[226:227], v72 offset:28256
	s_waitcnt lgkmcnt(8)
	v_mfma_f32_16x16x32_bf16 v[60:63], v[228:231], v[180:183], v[60:63]
	v_mfma_f32_16x16x32_bf16 v[28:31], v[228:231], v[184:187], v[28:31]
	s_waitcnt lgkmcnt(6)
	v_mfma_f32_16x16x32_bf16 v[34:37], v[232:235], v[188:191], v[34:37]
	v_mfma_f32_16x16x32_bf16 v[20:23], v[232:235], v[204:207], v[20:23]
	s_waitcnt lgkmcnt(4)
	v_mfma_f32_16x16x32_bf16 v[42:45], v[216:219], v[188:191], v[42:45]
	v_mfma_f32_16x16x32_bf16 v[24:27], v[216:219], v[204:207], v[24:27]
	s_waitcnt lgkmcnt(2)
	v_mfma_f32_16x16x32_bf16 v[56:59], v[220:223], v[188:191], v[56:59]
	v_mfma_f32_16x16x32_bf16 v[38:41], v[220:223], v[204:207], v[38:41]
	s_waitcnt lgkmcnt(0)
	v_mfma_f32_16x16x32_bf16 v[60:63], v[224:227], v[188:191], v[60:63]
	v_mfma_f32_16x16x32_bf16 v[28:31], v[224:227], v[204:207], v[28:31]
	s_branch .LBB0_666
.Lb_rare_B_0:
	v_max3_f32 v67, v88, v89, v90
	v_max3_f32 v67, v67, v91, v92
	v_max3_f32 v67, v67, v93, v94
	v_max3_f32 v67, v67, v95, v96
	v_max3_f32 v67, v67, v97, v98
	v_max3_f32 v67, v67, v99, v100
	v_max3_f32 v67, v67, v101, v102
	v_max_f32_e32 v67, v67, v103
	v_mov_b32_e32 v68, v67
	s_nop 1
	v_permlane16_swap_b32_e32 v67, v68
	v_max_f32_e32 v67, v67, v68
	v_mov_b32_e32 v68, v67
	s_nop 1
	v_permlane32_swap_b32_e32 v67, v68
	v_max_f32_e32 v67, v67, v68
	v_cmp_lt_f32_e32 vcc, s67, v67
	s_nop 1
	v_cndmask_b32_e32 v69, 0, v67, vcc
	v_sub_f32_e32 v70, 0, v69
	v_min_f32_e32 v70, 0, v70
	v_exp_f32_e32 v70, v70
	v_sub_f32_e32 v48, v48, v69
	v_sub_f32_e32 v49, v49, v69
	v_sub_f32_e32 v50, v50, v69
	v_sub_f32_e32 v51, v51, v69
	v_mul_f32_e32 v80, v80, v70
	v_mul_f32_e32 v34, v34, v70
	v_mul_f32_e32 v35, v35, v70
	v_mul_f32_e32 v36, v36, v70
	v_mul_f32_e32 v37, v37, v70
	v_mul_f32_e32 v42, v42, v70
	v_mul_f32_e32 v43, v43, v70
	v_mul_f32_e32 v44, v44, v70
	v_mul_f32_e32 v45, v45, v70
	v_mul_f32_e32 v56, v56, v70
	v_mul_f32_e32 v57, v57, v70
	v_mul_f32_e32 v58, v58, v70
	v_mul_f32_e32 v59, v59, v70
	v_mul_f32_e32 v60, v60, v70
	v_mul_f32_e32 v61, v61, v70
	v_mul_f32_e32 v62, v62, v70
	v_mul_f32_e32 v63, v63, v70
	v_sub_f32_e32 v88, v88, v69
	v_sub_f32_e32 v89, v89, v69
	v_sub_f32_e32 v90, v90, v69
	v_sub_f32_e32 v91, v91, v69
	v_sub_f32_e32 v92, v92, v69
	v_sub_f32_e32 v93, v93, v69
	v_sub_f32_e32 v94, v94, v69
	v_sub_f32_e32 v95, v95, v69
	v_sub_f32_e32 v96, v96, v69
	v_sub_f32_e32 v97, v97, v69
	v_sub_f32_e32 v98, v98, v69
	v_sub_f32_e32 v99, v99, v69
	v_sub_f32_e32 v100, v100, v69
	v_sub_f32_e32 v101, v101, v69
	v_sub_f32_e32 v102, v102, v69
	v_sub_f32_e32 v103, v103, v69
	v_exp_f32_e32 v236, v88
	v_exp_f32_e32 v237, v89
	v_exp_f32_e32 v238, v90
	v_exp_f32_e32 v239, v91
	v_exp_f32_e32 v240, v92
	v_exp_f32_e32 v241, v93
	v_exp_f32_e32 v242, v94
	v_exp_f32_e32 v243, v95
	v_exp_f32_e32 v244, v96
	v_exp_f32_e32 v245, v97
	v_exp_f32_e32 v246, v98
	v_exp_f32_e32 v247, v99
	v_exp_f32_e32 v248, v100
	v_exp_f32_e32 v249, v101
	v_exp_f32_e32 v250, v102
	v_exp_f32_e32 v251, v103
	s_nop 0
	v_add_f32_e32 v67, v236, v237
	v_add_f32_e32 v67, v67, v238
	v_add_f32_e32 v67, v67, v239
	v_add_f32_e32 v67, v67, v240
	v_add_f32_e32 v67, v67, v241
	v_add_f32_e32 v67, v67, v242
	v_add_f32_e32 v67, v67, v243
	v_add_f32_e32 v67, v67, v244
	v_add_f32_e32 v67, v67, v245
	v_add_f32_e32 v67, v67, v246
	v_add_f32_e32 v67, v67, v247
	v_add_f32_e32 v67, v67, v248
	v_add_f32_e32 v67, v67, v249
	v_add_f32_e32 v67, v67, v250
	v_add_f32_e32 v67, v67, v251
	s_branch .Lb_back_B_0
.Lb_rare_B_1:
	v_max3_f32 v67, v104, v105, v106
	v_max3_f32 v67, v67, v107, v168
	v_max3_f32 v67, v67, v169, v170
	v_max3_f32 v67, v67, v171, v172
	v_max3_f32 v67, v67, v173, v174
	v_max3_f32 v67, v67, v175, v176
	v_max3_f32 v67, v67, v177, v178
	v_max_f32_e32 v67, v67, v179
	v_mov_b32_e32 v68, v67
	s_nop 1
	v_permlane16_swap_b32_e32 v67, v68
	v_max_f32_e32 v67, v67, v68
	v_mov_b32_e32 v68, v67
	s_nop 1
	v_permlane32_swap_b32_e32 v67, v68
	v_max_f32_e32 v67, v67, v68
	v_cmp_lt_f32_e32 vcc, s67, v67
	s_nop 1
	v_cndmask_b32_e32 v69, 0, v67, vcc
	v_sub_f32_e32 v70, 0, v69
	v_min_f32_e32 v70, 0, v70
	v_exp_f32_e32 v70, v70
	v_sub_f32_e32 v52, v52, v69
	v_sub_f32_e32 v53, v53, v69
	v_sub_f32_e32 v54, v54, v69
	v_sub_f32_e32 v55, v55, v69
	v_mul_f32_e32 v64, v64, v70
	v_mul_f32_e32 v20, v20, v70
	v_mul_f32_e32 v21, v21, v70
	v_mul_f32_e32 v22, v22, v70
	v_mul_f32_e32 v23, v23, v70
	v_mul_f32_e32 v24, v24, v70
	v_mul_f32_e32 v25, v25, v70
	v_mul_f32_e32 v26, v26, v70
	v_mul_f32_e32 v27, v27, v70
	v_mul_f32_e32 v38, v38, v70
	v_mul_f32_e32 v39, v39, v70
	v_mul_f32_e32 v40, v40, v70
	v_mul_f32_e32 v41, v41, v70
	v_mul_f32_e32 v28, v28, v70
	v_mul_f32_e32 v29, v29, v70
	v_mul_f32_e32 v30, v30, v70
	v_mul_f32_e32 v31, v31, v70
	v_sub_f32_e32 v104, v104, v69
	v_sub_f32_e32 v105, v105, v69
	v_sub_f32_e32 v106, v106, v69
	v_sub_f32_e32 v107, v107, v69
	v_sub_f32_e32 v168, v168, v69
	v_sub_f32_e32 v169, v169, v69
	v_sub_f32_e32 v170, v170, v69
	v_sub_f32_e32 v171, v171, v69
	v_sub_f32_e32 v172, v172, v69
	v_sub_f32_e32 v173, v173, v69
	v_sub_f32_e32 v174, v174, v69
	v_sub_f32_e32 v175, v175, v69
	v_sub_f32_e32 v176, v176, v69
	v_sub_f32_e32 v177, v177, v69
	v_sub_f32_e32 v178, v178, v69
	v_sub_f32_e32 v179, v179, v69
	v_exp_f32_e32 v236, v104
	v_exp_f32_e32 v237, v105
	v_exp_f32_e32 v238, v106
	v_exp_f32_e32 v239, v107
	v_exp_f32_e32 v240, v168
	v_exp_f32_e32 v241, v169
	v_exp_f32_e32 v242, v170
	v_exp_f32_e32 v243, v171
	v_exp_f32_e32 v244, v172
	v_exp_f32_e32 v245, v173
	v_exp_f32_e32 v246, v174
	v_exp_f32_e32 v247, v175
	v_exp_f32_e32 v248, v176
	v_exp_f32_e32 v249, v177
	v_exp_f32_e32 v250, v178
	v_exp_f32_e32 v251, v179
	s_nop 0
	v_add_f32_e32 v67, v236, v237
	v_add_f32_e32 v67, v67, v238
	v_add_f32_e32 v67, v67, v239
	v_add_f32_e32 v67, v67, v240
	v_add_f32_e32 v67, v67, v241
	v_add_f32_e32 v67, v67, v242
	v_add_f32_e32 v67, v67, v243
	v_add_f32_e32 v67, v67, v244
	v_add_f32_e32 v67, v67, v245
	v_add_f32_e32 v67, v67, v246
	v_add_f32_e32 v67, v67, v247
	v_add_f32_e32 v67, v67, v248
	v_add_f32_e32 v67, v67, v249
	v_add_f32_e32 v67, v67, v250
	v_add_f32_e32 v67, v67, v251
	s_branch .Lb_back_B_1

.Lb_groupA:
	s_waitcnt vmcnt(0)
	v_mov_b32_e32 v34, 0
	v_mov_b32_e32 v35, 0
	v_mov_b32_e32 v36, 0
	v_mov_b32_e32 v37, 0
	v_mov_b32_e32 v42, 0
	v_mov_b32_e32 v43, 0
	v_mov_b32_e32 v44, 0
	v_mov_b32_e32 v45, 0
	v_mov_b32_e32 v56, 0
	v_mov_b32_e32 v57, 0
	v_mov_b32_e32 v58, 0
	v_mov_b32_e32 v59, 0
	v_mov_b32_e32 v60, 0
	v_mov_b32_e32 v61, 0
	v_mov_b32_e32 v62, 0
	v_mov_b32_e32 v63, 0
	v_mov_b32_e32 v20, 0
	v_mov_b32_e32 v21, 0
	v_mov_b32_e32 v22, 0
	v_mov_b32_e32 v23, 0
	v_mov_b32_e32 v24, 0
	v_mov_b32_e32 v25, 0
	v_mov_b32_e32 v26, 0
	v_mov_b32_e32 v27, 0
	v_mov_b32_e32 v38, 0
	v_mov_b32_e32 v39, 0
	v_mov_b32_e32 v40, 0
	v_mov_b32_e32 v41, 0
	v_mov_b32_e32 v28, 0
	v_mov_b32_e32 v29, 0
	v_mov_b32_e32 v30, 0
	v_mov_b32_e32 v31, 0
	v_mov_b32_e32 v180, 0
	v_mov_b32_e32 v181, 0
	v_mov_b32_e32 v182, 0
	v_mov_b32_e32 v183, 0
	v_mov_b32_e32 v184, 0
	v_mov_b32_e32 v185, 0
	v_mov_b32_e32 v186, 0
	v_mov_b32_e32 v187, 0
	v_mov_b32_e32 v188, 0
	v_mov_b32_e32 v189, 0
	v_mov_b32_e32 v190, 0
	v_mov_b32_e32 v191, 0
	v_mov_b32_e32 v204, 0
	v_mov_b32_e32 v205, 0
	v_mov_b32_e32 v206, 0
	v_mov_b32_e32 v207, 0
	v_mov_b32_e32 v48, 0
	v_mov_b32_e32 v49, 0
	v_mov_b32_e32 v50, 0
	v_mov_b32_e32 v51, 0
	v_mov_b32_e32 v52, 0
	v_mov_b32_e32 v53, 0
	v_mov_b32_e32 v54, 0
	v_mov_b32_e32 v55, 0
	v_mov_b32_e32 v80, 0
	v_mov_b32_e32 v64, 0
	v_add_u32_e32 v75, v116, v0
	s_mov_b32 s20, 0
	s_mov_b32 s42, 0
	s_mov_b32 s43, 0
	s_mov_b32 s51, 10240
	s_mov_b32 s30, 0xf8000
	s_mov_b32 s66, 0xff800000
	s_mov_b32 s67, 0xff800000
.Lb_loopA:
	s_and_b32 s8, s20, 1
	s_mul_i32 s32, s8, 10240
	s_xor_b32 s8, s8, 1
	s_mul_i32 s8, s8, 10240
	v_add_u32_e32 v71, s32, v75
	v_add_u32_e32 v73, s8, v120
	v_add_u32_e32 v72, s42, v119
	v_add_u32_e32 v74, s51, v120
	s_mov_b32 s19, 0
	s_mov_b32 s18, s30
	v_lshl_add_u64 v[208:209], v[112:113], 0, s[18:19]
	v_lshl_add_u64 v[212:213], v[114:115], 0, s[18:19]
	global_load_dwordx4 v[208:211], v[208:209], off
	global_load_dwordx4 v[212:215], v[212:213], off
	ds_read_b64_tr_b16 v[216:217], v72 offset:20480
	ds_read_b64_tr_b16 v[218:219], v72 offset:23040
	ds_read_b64_tr_b16 v[220:221], v72 offset:20512
	ds_read_b64_tr_b16 v[222:223], v72 offset:23072
	ds_read_b64_tr_b16 v[224:225], v72 offset:20544
	ds_read_b64_tr_b16 v[226:227], v72 offset:23104
	ds_read_b64_tr_b16 v[228:229], v72 offset:20576
	ds_read_b64_tr_b16 v[230:231], v72 offset:23136
	ds_read_b64_tr_b16 v[232:233], v72 offset:25600
	ds_read_b64_tr_b16 v[234:235], v72 offset:28160
	s_waitcnt lgkmcnt(8)
	v_mfma_f32_16x16x32_bf16 v[34:37], v[216:219], v[180:183], v[34:37]
	v_mfma_f32_16x16x32_bf16 v[20:23], v[216:219], v[184:187], v[20:23]
	ds_read_b64_tr_b16 v[216:217], v72 offset:25632
	ds_read_b64_tr_b16 v[218:219], v72 offset:28192
	s_waitcnt lgkmcnt(8)
	v_mfma_f32_16x16x32_bf16 v[42:45], v[220:223], v[180:183], v[42:45]
	v_mfma_f32_16x16x32_bf16 v[24:27], v[220:223], v[184:187], v[24:27]
	ds_read_b64_tr_b16 v[220:221], v72 offset:25664
	ds_read_b64_tr_b16 v[222:223], v72 offset:28224
	s_waitcnt lgkmcnt(8)
	v_mfma_f32_16x16x32_bf16 v[56:59], v[224:227], v[180:183], v[56:59]
	v_mfma_f32_16x16x32_bf16 v[38:41], v[224:227], v[184:187], v[38:41]
	ds_read_b64_tr_b16 v[224:225], v72 offset:25696
	ds_read_b64_tr_b16 v[226:227], v72 offset:28256
	s_waitcnt lgkmcnt(8)
	v_mfma_f32_16x16x32_bf16 v[60:63], v[228:231], v[180:183], v[60:63]
	v_mfma_f32_16x16x32_bf16 v[28:31], v[228:231], v[184:187], v[28:31]
	ds_read_b128 v[228:231], v71 offset:0
	s_waitcnt lgkmcnt(7)
	v_mfma_f32_16x16x32_bf16 v[34:37], v[232:235], v[188:191], v[34:37]
	v_mfma_f32_16x16x32_bf16 v[20:23], v[232:235], v[204:207], v[20:23]
	ds_read_b128 v[232:235], v71 offset:64
	s_waitcnt lgkmcnt(6)
	v_mfma_f32_16x16x32_bf16 v[42:45], v[216:219], v[188:191], v[42:45]
	v_mfma_f32_16x16x32_bf16 v[24:27], v[216:219], v[204:207], v[24:27]
	ds_read_b128 v[216:219], v71 offset:2560
	s_waitcnt lgkmcnt(5)
	v_mfma_f32_16x16x32_bf16 v[56:59], v[220:223], v[188:191], v[56:59]
	v_mfma_f32_16x16x32_bf16 v[38:41], v[220:223], v[204:207], v[38:41]
	ds_read_b128 v[220:223], v71 offset:2624
	s_waitcnt lgkmcnt(4)
	v_mfma_f32_16x16x32_bf16 v[60:63], v[224:227], v[188:191], v[60:63]
	v_mfma_f32_16x16x32_bf16 v[28:31], v[224:227], v[204:207], v[28:31]
	ds_read_b128 v[224:227], v71 offset:5120
	s_waitcnt lgkmcnt(4)
	v_mfma_f32_16x16x32_bf16 v[88:91], v[228:231], v[16:19], v[48:51]
	v_mfma_f32_16x16x32_bf16 v[104:107], v[228:231], v[12:15], v[52:55]
	ds_read_b128 v[228:231], v71 offset:5184
	s_waitcnt lgkmcnt(4)
	v_mfma_f32_16x16x32_bf16 v[88:91], v[232:235], v[8:11], v[88:91]
	v_mfma_f32_16x16x32_bf16 v[104:107], v[232:235], v[4:7], v[104:107]
	ds_read_b128 v[232:235], v71 offset:7680
	s_waitcnt lgkmcnt(4)
	v_mfma_f32_16x16x32_bf16 v[92:95], v[216:219], v[16:19], v[48:51]
	v_mfma_f32_16x16x32_bf16 v[168:171], v[216:219], v[12:15], v[52:55]
	ds_read_b128 v[216:219], v71 offset:7744
	s_waitcnt lgkmcnt(4)
	v_mfma_f32_16x16x32_bf16 v[92:95], v[220:223], v[8:11], v[92:95]
	v_mfma_f32_16x16x32_bf16 v[168:171], v[220:223], v[4:7], v[168:171]
	s_waitcnt lgkmcnt(3)
	v_mfma_f32_16x16x32_bf16 v[96:99], v[224:227], v[16:19], v[48:51]
	v_mfma_f32_16x16x32_bf16 v[172:175], v[224:227], v[12:15], v[52:55]
	s_waitcnt lgkmcnt(2)
	v_mfma_f32_16x16x32_bf16 v[96:99], v[228:231], v[8:11], v[96:99]
	v_mfma_f32_16x16x32_bf16 v[172:175], v[228:231], v[4:7], v[172:175]
	s_waitcnt lgkmcnt(1)
	v_mfma_f32_16x16x32_bf16 v[100:103], v[232:235], v[16:19], v[48:51]
	v_mfma_f32_16x16x32_bf16 v[176:179], v[232:235], v[12:15], v[52:55]
	s_waitcnt lgkmcnt(0)
	v_mfma_f32_16x16x32_bf16 v[100:103], v[216:219], v[8:11], v[100:103]
	v_mfma_f32_16x16x32_bf16 v[176:179], v[216:219], v[4:7], v[176:179]
	s_mov_b32 s42, s43
	s_mov_b32 s43, s51
	s_add_i32 s51, s51, 10240
	s_cmp_lg_u32 s51, 30720
	s_cselect_b32 s51, s51, 0
	s_min_u32 s8, s20, 61
	s_add_i32 s8, s8, 2
	s_mul_i32 s30, s8, 0xf8000
	s_nop 1
	v_exp_f32_e32 v236, v88
	v_exp_f32_e32 v237, v89
	v_exp_f32_e32 v238, v90
	v_exp_f32_e32 v239, v91
	v_exp_f32_e32 v240, v92
	v_exp_f32_e32 v241, v93
	v_exp_f32_e32 v242, v94
	v_exp_f32_e32 v243, v95
	v_exp_f32_e32 v244, v96
	v_exp_f32_e32 v245, v97
	v_exp_f32_e32 v246, v98
	v_exp_f32_e32 v247, v99
	v_exp_f32_e32 v248, v100
	v_exp_f32_e32 v249, v101
	v_exp_f32_e32 v250, v102
	v_exp_f32_e32 v251, v103
	s_nop 0
	v_add_f32_e32 v67, v236, v237
	v_add_f32_e32 v67, v67, v238
	v_add_f32_e32 v67, v67, v239
	v_add_f32_e32 v67, v67, v240
	v_add_f32_e32 v67, v67, v241
	v_add_f32_e32 v67, v67, v242
	v_add_f32_e32 v67, v67, v243
	v_add_f32_e32 v67, v67, v244
	v_add_f32_e32 v67, v67, v245
	v_add_f32_e32 v67, v67, v246
	v_add_f32_e32 v67, v67, v247
	v_add_f32_e32 v67, v67, v248
	v_add_f32_e32 v67, v67, v249
	v_add_f32_e32 v67, v67, v250
	v_add_f32_e32 v67, v67, v251
	v_cmp_lt_f32_e32 vcc, s66, v67
	s_cbranch_vccnz .Lb_rare_A_0

.Lb_back_A_1:
	v_add_f32_e32 v64, v64, v67
	v_cvt_pk_bf16_f32 v184, v236, v237
	v_cvt_pk_bf16_f32 v185, v238, v239
	v_cvt_pk_bf16_f32 v186, v240, v241
	v_cvt_pk_bf16_f32 v187, v242, v243
	v_cvt_pk_bf16_f32 v204, v244, v245
	v_cvt_pk_bf16_f32 v205, v246, v247
	v_cvt_pk_bf16_f32 v206, v248, v249
	v_cvt_pk_bf16_f32 v207, v250, v251
	s_waitcnt vmcnt(0)
	ds_write_b128 v73, v[208:211]
	ds_write_b128 v74, v[212:215] offset:20480
	s_mov_b32 s66, 0x5f800000
	s_mov_b32 s67, 0x42000000
	s_add_i32 s20, s20, 1
	s_waitcnt lgkmcnt(0)
	s_barrier
	s_cmp_lt_u32 s20, 64
	s_cbranch_scc1 .Lb_loopA
	v_add_u32_e32 v72, s42, v119
	ds_read_b64_tr_b16 v[216:217], v72 offset:20480
	ds_read_b64_tr_b16 v[218:219], v72 offset:23040
	ds_read_b64_tr_b16 v[220:221], v72 offset:20512
	ds_read_b64_tr_b16 v[222:223], v72 offset:23072
	ds_read_b64_tr_b16 v[224:225], v72 offset:20544
	ds_read_b64_tr_b16 v[226:227], v72 offset:23104
	ds_read_b64_tr_b16 v[228:229], v72 offset:20576
	ds_read_b64_tr_b16 v[230:231], v72 offset:23136
	ds_read_b64_tr_b16 v[232:233], v72 offset:25600
	ds_read_b64_tr_b16 v[234:235], v72 offset:28160
	s_waitcnt lgkmcnt(8)
	v_mfma_f32_16x16x32_bf16 v[34:37], v[216:219], v[180:183], v[34:37]
	v_mfma_f32_16x16x32_bf16 v[20:23], v[216:219], v[184:187], v[20:23]
	ds_read_b64_tr_b16 v[216:217], v72 offset:25632
	ds_read_b64_tr_b16 v[218:219], v72 offset:28192
	s_waitcnt lgkmcnt(8)
	v_mfma_f32_16x16x32_bf16 v[42:45], v[220:223], v[180:183], v[42:45]
	v_mfma_f32_16x16x32_bf16 v[24:27], v[220:223], v[184:187], v[24:27]
	ds_read_b64_tr_b16 v[220:221], v72 offset:25664
	ds_read_b64_tr_b16 v[222:223], v72 offset:28224
	s_waitcnt lgkmcnt(8)
	v_mfma_f32_16x16x32_bf16 v[56:59], v[224:227], v[180:183], v[56:59]
	v_mfma_f32_16x16x32_bf16 v[38:41], v[224:227], v[184:187], v[38:41]
	ds_read_b64_tr_b16 v[224:225], v72 offset:25696
	ds_read_b64_tr_b16 v[226:227], v72 offset:28256
	s_waitcnt lgkmcnt(8)
	v_mfma_f32_16x16x32_bf16 v[60:63], v[228:231], v[180:183], v[60:63]
	v_mfma_f32_16x16x32_bf16 v[28:31], v[228:231], v[184:187], v[28:31]
	s_waitcnt lgkmcnt(6)
	v_mfma_f32_16x16x32_bf16 v[34:37], v[232:235], v[188:191], v[34:37]
	v_mfma_f32_16x16x32_bf16 v[20:23], v[232:235], v[204:207], v[20:23]
	s_waitcnt lgkmcnt(4)
	v_mfma_f32_16x16x32_bf16 v[42:45], v[216:219], v[188:191], v[42:45]
	v_mfma_f32_16x16x32_bf16 v[24:27], v[216:219], v[204:207], v[24:27]
	s_waitcnt lgkmcnt(2)
	v_mfma_f32_16x16x32_bf16 v[56:59], v[220:223], v[188:191], v[56:59]
	v_mfma_f32_16x16x32_bf16 v[38:41], v[220:223], v[204:207], v[38:41]
	s_waitcnt lgkmcnt(0)
	v_mfma_f32_16x16x32_bf16 v[60:63], v[224:227], v[188:191], v[60:63]
	v_mfma_f32_16x16x32_bf16 v[28:31], v[224:227], v[204:207], v[28:31]
